# FoX: a wave prepares its first (diagonal) score tile one iteration early, in the iteration where it is otherwise idle, instead of stalling the other waves
# baseline (speedup 1.0000x reference)
.LBB0_180:
	s_add_i32 s37, s46, 1
	s_cmp_eq_u32 s47, s37
	s_cbranch_scc1 .Lfx_first_early
	s_cmp_gt_i32 s47, s46
	s_cbranch_scc1 .LBB0_188
	s_cmp_lg_u32 s46, s47
	s_cbranch_scc1 .Lfx_body
	s_lshr_b32 s37, s44, 6
	s_or_b32 s37, s37, 3
	s_cmp_lg_u32 s46, s37
	s_cbranch_scc1 .Lfx_body
	v_add_u32_e32 v1, s48, v189
	ds_read_b128 v[126:129], v1 offset:32768
	ds_read_b128 v[106:109], v1 offset:40960
	ds_read_b128 v[98:101], v1 offset:33792
	ds_read_b128 v[102:105], v1 offset:41984
	ds_read_b128 v[86:89], v1 offset:34816
	ds_read_b128 v[94:97], v1 offset:43008
	ds_read_b128 v[82:85], v1 offset:35840
	ds_read_b128 v[90:93], v1 offset:44032
	ds_read_b128 v[34:37], v175
	ds_read_b128 v[38:41], v175 offset:16
	ds_read_b128 v[42:45], v175 offset:64
	ds_read_b128 v[46:49], v175 offset:80
	ds_read_b128 v[50:53], v175 offset:128
	ds_read_b128 v[54:57], v175 offset:144
	ds_read_b128 v[58:61], v175 offset:192
	ds_read_b128 v[62:65], v175 offset:208
	s_waitcnt lgkmcnt(0)
	v_mfma_f32_32x32x16_bf16 v[34:49], v[126:129], v[66:69], v[34:49]
	v_mfma_f32_32x32x16_bf16 v[50:65], v[106:109], v[66:69], v[50:65]
	v_mfma_f32_32x32x16_bf16 v[34:49], v[98:101], v[70:73], v[34:49]
	v_mfma_f32_32x32x16_bf16 v[50:65], v[102:105], v[70:73], v[50:65]
	v_mfma_f32_32x32x16_bf16 v[34:49], v[86:89], v[74:77], v[34:49]
	v_mfma_f32_32x32x16_bf16 v[50:65], v[94:97], v[74:77], v[50:65]
	v_mfma_f32_32x32x16_bf16 v[34:49], v[82:85], v[78:81], v[34:49]
	v_mfma_f32_32x32x16_bf16 v[50:65], v[90:93], v[78:81], v[50:65]
	s_nop 1
	v_add_u32_e32 v1, s50, v166
	v_add_u32_e32 v163, 0xe0, v1
	v_add_u32_e32 v162, 0xc0, v1
	v_cmp_le_i32_e32 vcc, v163, v186
	s_nop 6
	v_cndmask_b32_e32 v50, v239, v50, vcc
	v_cmp_lt_i32_e32 vcc, v162, v186
	s_nop 1
	v_cndmask_b32_e32 v35, v239, v35, vcc
	v_cmp_le_i32_e32 vcc, v162, v186
	v_add_u32_e32 v162, 0xe1, v1
	s_nop 0
	v_cndmask_b32_e32 v34, v239, v34, vcc
	v_cmp_le_i32_e32 vcc, v162, v186
	v_add_u32_e32 v162, 0xc2, v1
	s_nop 0
	v_cndmask_b32_e32 v51, v239, v51, vcc
	v_cmp_le_i32_e32 vcc, v162, v186
	v_add_u32_e32 v162, 0xe2, v1
	s_nop 0
	v_cndmask_b32_e32 v36, v239, v36, vcc
	v_cmp_le_i32_e32 vcc, v162, v186
	v_add_u32_e32 v162, 0xc3, v1
	s_nop 0
	v_cndmask_b32_e32 v52, v239, v52, vcc
	v_cmp_le_i32_e32 vcc, v162, v186
	v_add_u32_e32 v162, 0xe3, v1
	s_nop 0
	v_cndmask_b32_e32 v37, v239, v37, vcc
	v_cmp_le_i32_e32 vcc, v162, v186
	v_add_u32_e32 v162, 0xc4, v1
	s_nop 0
	v_cndmask_b32_e32 v53, v239, v53, vcc
	v_cmp_le_i32_e32 vcc, v162, v186
	v_add_u32_e32 v162, 0xe4, v1
	s_nop 0
	v_cndmask_b32_e32 v38, v239, v38, vcc
	v_cmp_le_i32_e32 vcc, v162, v186
	v_add_u32_e32 v162, 0xc5, v1
	s_nop 0
	v_cndmask_b32_e32 v54, v239, v54, vcc
	v_cmp_le_i32_e32 vcc, v162, v186
	v_add_u32_e32 v162, 0xe5, v1
	s_nop 0
	v_cndmask_b32_e32 v39, v239, v39, vcc
	v_cmp_le_i32_e32 vcc, v162, v186
	v_add_u32_e32 v162, 0xc6, v1
	s_nop 0
	v_cndmask_b32_e32 v55, v239, v55, vcc
	v_cmp_le_i32_e32 vcc, v162, v186
	v_add_u32_e32 v162, 0xe6, v1
	s_nop 0
	v_cndmask_b32_e32 v40, v239, v40, vcc
	v_cmp_le_i32_e32 vcc, v162, v186
	v_add_u32_e32 v162, 0xc7, v1
	s_nop 0
	v_cndmask_b32_e32 v56, v239, v56, vcc
	v_cmp_le_i32_e32 vcc, v162, v186
	v_add_u32_e32 v162, 0xe7, v1
	s_nop 0
	v_cndmask_b32_e32 v41, v239, v41, vcc
	v_cmp_le_i32_e32 vcc, v162, v186
	v_add_u32_e32 v162, 0xd0, v1
	s_nop 0
	v_cndmask_b32_e32 v57, v239, v57, vcc
	v_cmp_le_i32_e32 vcc, v162, v186
	v_add_u32_e32 v162, 0xf0, v1
	s_nop 0
	v_cndmask_b32_e32 v42, v239, v42, vcc
	v_cmp_le_i32_e32 vcc, v162, v186
	v_add_u32_e32 v162, 0xd1, v1
	s_nop 0
	v_cndmask_b32_e32 v58, v239, v58, vcc
	v_cmp_le_i32_e32 vcc, v162, v186
	v_add_u32_e32 v162, 0xf1, v1
	s_nop 0
	v_cndmask_b32_e32 v43, v239, v43, vcc
	v_cmp_le_i32_e32 vcc, v162, v186
	v_add_u32_e32 v162, 0xd2, v1
	s_nop 0
	v_cndmask_b32_e32 v59, v239, v59, vcc
	v_cmp_le_i32_e32 vcc, v162, v186
	v_add_u32_e32 v162, 0xf2, v1
	s_nop 0
	v_cndmask_b32_e32 v44, v239, v44, vcc
	v_cmp_le_i32_e32 vcc, v162, v186
	v_add_u32_e32 v162, 0xd3, v1
	s_nop 0
	v_cndmask_b32_e32 v60, v239, v60, vcc
	v_cmp_le_i32_e32 vcc, v162, v186
	v_add_u32_e32 v162, 0xf3, v1
	s_nop 0
	v_cndmask_b32_e32 v45, v239, v45, vcc
	v_cmp_le_i32_e32 vcc, v162, v186
	v_add_u32_e32 v162, 0xd4, v1
	s_nop 0
	v_cndmask_b32_e32 v61, v239, v61, vcc
	v_cmp_le_i32_e32 vcc, v162, v186
	v_add_u32_e32 v162, 0xf4, v1
	s_nop 0
	v_cndmask_b32_e32 v46, v239, v46, vcc
	v_cmp_le_i32_e32 vcc, v162, v186
	v_add_u32_e32 v162, 0xd5, v1
	s_nop 0
	v_cndmask_b32_e32 v62, v239, v62, vcc
	v_cmp_le_i32_e32 vcc, v162, v186
	v_add_u32_e32 v162, 0xf5, v1
	s_nop 0
	v_cndmask_b32_e32 v47, v239, v47, vcc
	v_cmp_le_i32_e32 vcc, v162, v186
	v_add_u32_e32 v162, 0xd6, v1
	s_nop 0
	v_cndmask_b32_e32 v63, v239, v63, vcc
	v_cmp_le_i32_e32 vcc, v162, v186
	v_add_u32_e32 v162, 0xf6, v1
	s_nop 0
	v_cndmask_b32_e32 v48, v239, v48, vcc
	v_cmp_le_i32_e32 vcc, v162, v186
	v_add_u32_e32 v162, 0xd7, v1
	v_add_u32_e32 v1, 0xf7, v1
	v_cndmask_b32_e32 v64, v239, v64, vcc
	v_cmp_le_i32_e32 vcc, v162, v186
	s_nop 1
	v_cndmask_b32_e32 v49, v239, v49, vcc
	v_cmp_le_i32_e32 vcc, v1, v186
	s_nop 1
	v_cndmask_b32_e32 v65, v239, v65, vcc
	v_mov_b32_e32 v163, v0
	v_max3_f32 v1, v34, v35, v36
	v_max3_f32 v208, v50, v51, v52
	v_max3_f32 v1, v1, v37, v38
	v_max3_f32 v1, v1, v39, v40
	v_max3_f32 v1, v1, v41, v42
	v_max3_f32 v1, v1, v43, v44
	v_max3_f32 v1, v1, v45, v46
	v_max3_f32 v1, v1, v47, v48
	v_max3_f32 v208, v208, v53, v54
	v_max3_f32 v208, v208, v55, v56
	v_max3_f32 v208, v208, v57, v58
	v_max3_f32 v208, v208, v59, v60
	v_max3_f32 v208, v208, v61, v62
	v_max3_f32 v208, v208, v63, v64
	v_max3_f32 v208, v208, v65, v49
	v_max_f32_e32 v1, v1, v208
	ds_bpermute_b32 v209, v203, v1
	s_waitcnt lgkmcnt(0)
	v_max_f32_e32 v1, v1, v209
	v_cvt_pk_bf16_f32 v209, v1, v1
	v_lshlrev_b32_e32 v200, 16, v209
	v_xor_b32_e32 v209, 0x8000, v209
	v_and_b32_e32 v209, 0xffff, v209
	v_cndmask_b32_e64 v162, 0, v209, s[16:17]
	v_sub_f32_e32 v34, v34, v200
	v_sub_f32_e32 v35, v35, v200
	v_sub_f32_e32 v36, v36, v200
	v_sub_f32_e32 v37, v37, v200
	v_sub_f32_e32 v38, v38, v200
	v_sub_f32_e32 v39, v39, v200
	v_sub_f32_e32 v40, v40, v200
	v_sub_f32_e32 v41, v41, v200
	v_sub_f32_e32 v42, v42, v200
	v_sub_f32_e32 v43, v43, v200
	v_sub_f32_e32 v44, v44, v200
	v_sub_f32_e32 v45, v45, v200
	v_sub_f32_e32 v46, v46, v200
	v_sub_f32_e32 v47, v47, v200
	v_sub_f32_e32 v48, v48, v200
	v_sub_f32_e32 v49, v49, v200
	v_sub_f32_e32 v50, v50, v200
	v_sub_f32_e32 v51, v51, v200
	v_sub_f32_e32 v52, v52, v200
	v_sub_f32_e32 v53, v53, v200
	v_sub_f32_e32 v54, v54, v200
	v_sub_f32_e32 v55, v55, v200
	v_sub_f32_e32 v56, v56, v200
	v_sub_f32_e32 v57, v57, v200
	v_sub_f32_e32 v58, v58, v200
	v_sub_f32_e32 v59, v59, v200
	v_sub_f32_e32 v60, v60, v200
	v_sub_f32_e32 v61, v61, v200
	v_sub_f32_e32 v62, v62, v200
	v_sub_f32_e32 v63, v63, v200
	v_sub_f32_e32 v64, v64, v200
	v_sub_f32_e32 v65, v65, v200

.Lfx_first_early:
	v_add_u32_e32 v195, 0xffffff00, v175
	v_max_i32_e32 v195, v195, v0
	v_add_u32_e32 v1, s48, v189
	ds_read_b128 v[126:129], v1 offset:32768
	ds_read_b128 v[106:109], v1 offset:40960
	ds_read_b128 v[98:101], v1 offset:33792
	ds_read_b128 v[102:105], v1 offset:41984
	ds_read_b128 v[86:89], v1 offset:34816
	ds_read_b128 v[94:97], v1 offset:43008
	ds_read_b128 v[82:85], v1 offset:35840
	ds_read_b128 v[90:93], v1 offset:44032
	ds_read_b128 v[34:37], v195
	ds_read_b128 v[38:41], v195 offset:16
	ds_read_b128 v[42:45], v195 offset:64
	ds_read_b128 v[46:49], v195 offset:80
	ds_read_b128 v[50:53], v195 offset:128
	ds_read_b128 v[54:57], v195 offset:144
	ds_read_b128 v[58:61], v195 offset:192
	ds_read_b128 v[62:65], v195 offset:208
	s_waitcnt lgkmcnt(0)
	v_mfma_f32_32x32x16_bf16 v[34:49], v[126:129], v[66:69], v[34:49]
	v_mfma_f32_32x32x16_bf16 v[50:65], v[106:109], v[66:69], v[50:65]
	v_mfma_f32_32x32x16_bf16 v[34:49], v[98:101], v[70:73], v[34:49]
	v_mfma_f32_32x32x16_bf16 v[50:65], v[102:105], v[70:73], v[50:65]
	v_mfma_f32_32x32x16_bf16 v[34:49], v[86:89], v[74:77], v[34:49]
	v_mfma_f32_32x32x16_bf16 v[50:65], v[94:97], v[74:77], v[50:65]
	v_mfma_f32_32x32x16_bf16 v[34:49], v[82:85], v[78:81], v[34:49]
	v_mfma_f32_32x32x16_bf16 v[50:65], v[90:93], v[78:81], v[50:65]
	s_nop 1
	s_add_i32 s37, s50, 0xffffffc0
	v_add_u32_e32 v1, s37, v166
	v_add_u32_e32 v163, 0xe0, v1
	v_add_u32_e32 v162, 0xc0, v1
	v_cmp_le_i32_e32 vcc, v163, v186
	s_nop 6
	v_cndmask_b32_e32 v50, v239, v50, vcc
	v_cmp_lt_i32_e32 vcc, v162, v186
	s_nop 1
	v_cndmask_b32_e32 v35, v239, v35, vcc
	v_cmp_le_i32_e32 vcc, v162, v186
	v_add_u32_e32 v162, 0xe1, v1
	s_nop 0
	v_cndmask_b32_e32 v34, v239, v34, vcc
	v_cmp_le_i32_e32 vcc, v162, v186
	v_add_u32_e32 v162, 0xc2, v1
	s_nop 0
	v_cndmask_b32_e32 v51, v239, v51, vcc
	v_cmp_le_i32_e32 vcc, v162, v186
	v_add_u32_e32 v162, 0xe2, v1
	s_nop 0
	v_cndmask_b32_e32 v36, v239, v36, vcc
	v_cmp_le_i32_e32 vcc, v162, v186
	v_add_u32_e32 v162, 0xc3, v1
	s_nop 0
	v_cndmask_b32_e32 v52, v239, v52, vcc
	v_cmp_le_i32_e32 vcc, v162, v186
	v_add_u32_e32 v162, 0xe3, v1
	s_nop 0
	v_cndmask_b32_e32 v37, v239, v37, vcc
	v_cmp_le_i32_e32 vcc, v162, v186
	v_add_u32_e32 v162, 0xc4, v1
	s_nop 0
	v_cndmask_b32_e32 v53, v239, v53, vcc
	v_cmp_le_i32_e32 vcc, v162, v186
	v_add_u32_e32 v162, 0xe4, v1
	s_nop 0
	v_cndmask_b32_e32 v38, v239, v38, vcc
	v_cmp_le_i32_e32 vcc, v162, v186
	v_add_u32_e32 v162, 0xc5, v1
	s_nop 0
	v_cndmask_b32_e32 v54, v239, v54, vcc
	v_cmp_le_i32_e32 vcc, v162, v186
	v_add_u32_e32 v162, 0xe5, v1
	s_nop 0
	v_cndmask_b32_e32 v39, v239, v39, vcc
	v_cmp_le_i32_e32 vcc, v162, v186
	v_add_u32_e32 v162, 0xc6, v1
	s_nop 0
	v_cndmask_b32_e32 v55, v239, v55, vcc
	v_cmp_le_i32_e32 vcc, v162, v186
	v_add_u32_e32 v162, 0xe6, v1
	s_nop 0
	v_cndmask_b32_e32 v40, v239, v40, vcc
	v_cmp_le_i32_e32 vcc, v162, v186
	v_add_u32_e32 v162, 0xc7, v1
	s_nop 0
	v_cndmask_b32_e32 v56, v239, v56, vcc
	v_cmp_le_i32_e32 vcc, v162, v186
	v_add_u32_e32 v162, 0xe7, v1
	s_nop 0
	v_cndmask_b32_e32 v41, v239, v41, vcc
	v_cmp_le_i32_e32 vcc, v162, v186
	v_add_u32_e32 v162, 0xd0, v1
	s_nop 0
	v_cndmask_b32_e32 v57, v239, v57, vcc
	v_cmp_le_i32_e32 vcc, v162, v186
	v_add_u32_e32 v162, 0xf0, v1
	s_nop 0
	v_cndmask_b32_e32 v42, v239, v42, vcc
	v_cmp_le_i32_e32 vcc, v162, v186
	v_add_u32_e32 v162, 0xd1, v1
	s_nop 0
	v_cndmask_b32_e32 v58, v239, v58, vcc
	v_cmp_le_i32_e32 vcc, v162, v186
	v_add_u32_e32 v162, 0xf1, v1
	s_nop 0
	v_cndmask_b32_e32 v43, v239, v43, vcc
	v_cmp_le_i32_e32 vcc, v162, v186
	v_add_u32_e32 v162, 0xd2, v1
	s_nop 0
	v_cndmask_b32_e32 v59, v239, v59, vcc
	v_cmp_le_i32_e32 vcc, v162, v186
	v_add_u32_e32 v162, 0xf2, v1
	s_nop 0
	v_cndmask_b32_e32 v44, v239, v44, vcc
	v_cmp_le_i32_e32 vcc, v162, v186
	v_add_u32_e32 v162, 0xd3, v1
	s_nop 0
	v_cndmask_b32_e32 v60, v239, v60, vcc
	v_cmp_le_i32_e32 vcc, v162, v186
	v_add_u32_e32 v162, 0xf3, v1
	s_nop 0
	v_cndmask_b32_e32 v45, v239, v45, vcc
	v_cmp_le_i32_e32 vcc, v162, v186
	v_add_u32_e32 v162, 0xd4, v1
	s_nop 0
	v_cndmask_b32_e32 v61, v239, v61, vcc
	v_cmp_le_i32_e32 vcc, v162, v186
	v_add_u32_e32 v162, 0xf4, v1
	s_nop 0
	v_cndmask_b32_e32 v46, v239, v46, vcc
	v_cmp_le_i32_e32 vcc, v162, v186
	v_add_u32_e32 v162, 0xd5, v1
	s_nop 0
	v_cndmask_b32_e32 v62, v239, v62, vcc
	v_cmp_le_i32_e32 vcc, v162, v186
	v_add_u32_e32 v162, 0xf5, v1
	s_nop 0
	v_cndmask_b32_e32 v47, v239, v47, vcc
	v_cmp_le_i32_e32 vcc, v162, v186
	v_add_u32_e32 v162, 0xd6, v1
	s_nop 0
	v_cndmask_b32_e32 v63, v239, v63, vcc
	v_cmp_le_i32_e32 vcc, v162, v186
	v_add_u32_e32 v162, 0xf6, v1
	s_nop 0
	v_cndmask_b32_e32 v48, v239, v48, vcc
	v_cmp_le_i32_e32 vcc, v162, v186
	v_add_u32_e32 v162, 0xd7, v1
	v_add_u32_e32 v1, 0xf7, v1
	v_cndmask_b32_e32 v64, v239, v64, vcc
	v_cmp_le_i32_e32 vcc, v162, v186
	s_nop 1
	v_cndmask_b32_e32 v49, v239, v49, vcc
	v_cmp_le_i32_e32 vcc, v1, v186
	s_nop 1
	v_cndmask_b32_e32 v65, v239, v65, vcc
	v_mov_b32_e32 v163, v0
	v_max3_f32 v1, v34, v35, v36
	v_max3_f32 v208, v50, v51, v52
	v_max3_f32 v1, v1, v37, v38
	v_max3_f32 v1, v1, v39, v40
	v_max3_f32 v1, v1, v41, v42
	v_max3_f32 v1, v1, v43, v44
	v_max3_f32 v1, v1, v45, v46
	v_max3_f32 v1, v1, v47, v48
	v_max3_f32 v208, v208, v53, v54
	v_max3_f32 v208, v208, v55, v56
	v_max3_f32 v208, v208, v57, v58
	v_max3_f32 v208, v208, v59, v60
	v_max3_f32 v208, v208, v61, v62
	v_max3_f32 v208, v208, v63, v64
	v_max3_f32 v208, v208, v65, v49
	v_max_f32_e32 v1, v1, v208
	ds_bpermute_b32 v209, v203, v1
	s_waitcnt lgkmcnt(0)
	v_max_f32_e32 v1, v1, v209
	v_cvt_pk_bf16_f32 v209, v1, v1
	v_lshlrev_b32_e32 v200, 16, v209
	v_xor_b32_e32 v209, 0x8000, v209
	v_and_b32_e32 v209, 0xffff, v209
	v_cndmask_b32_e64 v162, 0, v209, s[16:17]
	v_sub_f32_e32 v34, v34, v200
	v_sub_f32_e32 v35, v35, v200
	v_sub_f32_e32 v36, v36, v200
	v_sub_f32_e32 v37, v37, v200
	v_sub_f32_e32 v38, v38, v200
	v_sub_f32_e32 v39, v39, v200
	v_sub_f32_e32 v40, v40, v200
	v_sub_f32_e32 v41, v41, v200
	v_sub_f32_e32 v42, v42, v200
	v_sub_f32_e32 v43, v43, v200
	v_sub_f32_e32 v44, v44, v200
	v_sub_f32_e32 v45, v45, v200
	v_sub_f32_e32 v46, v46, v200
	v_sub_f32_e32 v47, v47, v200
	v_sub_f32_e32 v48, v48, v200
	v_sub_f32_e32 v49, v49, v200
	v_sub_f32_e32 v50, v50, v200
	v_sub_f32_e32 v51, v51, v200
	v_sub_f32_e32 v52, v52, v200
	v_sub_f32_e32 v53, v53, v200
	v_sub_f32_e32 v54, v54, v200
	v_sub_f32_e32 v55, v55, v200
	v_sub_f32_e32 v56, v56, v200
	v_sub_f32_e32 v57, v57, v200
	v_sub_f32_e32 v58, v58, v200
	v_sub_f32_e32 v59, v59, v200
	v_sub_f32_e32 v60, v60, v200
	v_sub_f32_e32 v61, v61, v200
	v_sub_f32_e32 v62, v62, v200
	v_sub_f32_e32 v63, v63, v200
	v_sub_f32_e32 v64, v64, v200
	v_sub_f32_e32 v65, v65, v200
	s_branch .LBB0_188
